# accumulators zeroed with 64 v_mov_b64 instead of 128 v_mov_b32 per GEMM tile
# speedup vs baseline: 1.0224x; 1.0044x over previous
; template <class Epi, class Sched, bool ALIGN_EPI = false, bool SP2 = false>
; __device__ __forceinline__ void gemm_phase(PG8_LAS unsigned char* lds, const Gemm g, const Sched& S, const Epi& E) {
;     ...
;         const bool has_next = S.next(ui + 1, nxt);
;         const char* nA = has_next ? (const char*)g.A + (size_t)nxt.pm * tstepA : cA; const char* nB = has_next ? (const char*)g.Bt + (size_t)nxt.pn * tstepB : cB;
;     ...
; #pragma unroll
;         for (int a = 0; a < 2; ++a)
; #pragma unroll
;             for (int b = 0; b < 2; ++b)
; #pragma unroll
;                 for (int m = 0; m < 4; ++m)
; #pragma unroll
;                     for (int n = 0; n < 2; ++n) acc[a][b][m][n] = (f32x4){0.f, 0.f, 0.f, 0.f};
;         cur = nxt; cA = nA; cB = nB; ++ui;
.LBB0_140:
	s_ashr_i32 s59, s58, 31
	s_lshl_b64 s[60:61], s[58:59], 19
	s_add_u32 s60, s12, s60
	s_addc_u32 s61, s13, s61
	s_and_b64 s[62:63], s[2:3], exec
	s_cselect_b32 s59, s61, s71
	s_cselect_b32 s92, s60, s70
	s_ashr_i32 s57, s56, 31
	s_lshl_b64 s[62:63], s[56:57], 19
	s_add_u32 s62, s80, s62
	s_addc_u32 s63, s81, s63
	s_and_b64 s[94:95], s[2:3], exec
	s_cselect_b32 s57, s63, s73
	s_cselect_b32 s93, s62, s72
	s_add_u32 s70, s70, 0x10000
	s_addc_u32 s71, s71, 0
	s_add_u32 s72, s72, 0x10000
	v_mov_b64_e32 v[0:1], 0
	v_mov_b64_e32 v[2:3], 0
	v_mov_b64_e32 v[4:5], 0
	v_mov_b64_e32 v[6:7], 0
	v_mov_b64_e32 v[8:9], 0
	v_mov_b64_e32 v[10:11], 0
	v_mov_b64_e32 v[12:13], 0
	v_mov_b64_e32 v[14:15], 0
	v_mov_b64_e32 v[16:17], 0
	v_mov_b64_e32 v[18:19], 0
	v_mov_b64_e32 v[20:21], 0
	v_mov_b64_e32 v[22:23], 0
	v_mov_b64_e32 v[24:25], 0
	v_mov_b64_e32 v[26:27], 0
	v_mov_b64_e32 v[28:29], 0
	v_mov_b64_e32 v[30:31], 0
	v_mov_b64_e32 v[32:33], 0
	v_mov_b64_e32 v[34:35], 0
	v_mov_b64_e32 v[36:37], 0
	v_mov_b64_e32 v[38:39], 0
	v_mov_b64_e32 v[40:41], 0
	v_mov_b64_e32 v[42:43], 0
	v_mov_b64_e32 v[44:45], 0
	v_mov_b64_e32 v[46:47], 0
	v_mov_b64_e32 v[48:49], 0
	v_mov_b64_e32 v[50:51], 0
	v_mov_b64_e32 v[52:53], 0
	v_mov_b64_e32 v[54:55], 0
	v_mov_b64_e32 v[56:57], 0
	v_mov_b64_e32 v[58:59], 0
	v_mov_b64_e32 v[60:61], 0
	v_mov_b64_e32 v[62:63], 0
	v_mov_b64_e32 v[64:65], 0
	v_mov_b64_e32 v[66:67], 0
	v_mov_b64_e32 v[68:69], 0
	v_mov_b64_e32 v[70:71], 0
	v_mov_b64_e32 v[72:73], 0
	v_mov_b64_e32 v[74:75], 0
	v_mov_b64_e32 v[76:77], 0
	v_mov_b64_e32 v[78:79], 0
	v_mov_b64_e32 v[80:81], 0
	v_mov_b64_e32 v[82:83], 0
	v_mov_b64_e32 v[84:85], 0
	v_mov_b64_e32 v[86:87], 0
	v_mov_b64_e32 v[88:89], 0
	v_mov_b64_e32 v[90:91], 0
	v_mov_b64_e32 v[92:93], 0
	v_mov_b64_e32 v[94:95], 0
	v_mov_b64_e32 v[96:97], 0
	v_mov_b64_e32 v[98:99], 0
	v_mov_b64_e32 v[100:101], 0
	v_mov_b64_e32 v[102:103], 0
	v_mov_b64_e32 v[104:105], 0
	v_mov_b64_e32 v[106:107], 0
	v_mov_b64_e32 v[108:109], 0
	v_mov_b64_e32 v[110:111], 0
	v_mov_b64_e32 v[112:113], 0
	v_mov_b64_e32 v[114:115], 0
	v_mov_b64_e32 v[116:117], 0
	v_mov_b64_e32 v[118:119], 0
	v_mov_b64_e32 v[120:121], 0
	v_mov_b64_e32 v[122:123], 0
	v_mov_b64_e32 v[124:125], 0
	v_mov_b64_e32 v[126:127], 0
	s_addc_u32 s73, s73, 0
	s_mov_b32 s94, -2

; template <class Epi, class Sched, bool ALIGN_EPI = false, bool SP2 = false>
; __device__ __forceinline__ void gemm_phase(PG8_LAS unsigned char* lds, const Gemm g, const Sched& S, const Epi& E) {
;     ...
; #pragma unroll
;         for (int a = 0; a < 2; ++a)
; #pragma unroll
;             for (int b = 0; b < 2; ++b)
; #pragma unroll
;                 for (int m = 0; m < 4; ++m)
; #pragma unroll
;                     for (int n = 0; n < 2; ++n) acc[a][b][m][n] = (f32x4){0.f, 0.f, 0.f, 0.f};
;         cur = nxt; cA = nA; cB = nB; ++ui;
.LBB0_225:
	s_add_u32 s68, s68, 0x10000
	s_addc_u32 s69, s69, 0
	s_add_u32 s70, s70, 0x10000
	v_mov_b64_e32 v[0:1], 0
	v_mov_b64_e32 v[2:3], 0
	v_mov_b64_e32 v[4:5], 0
	v_mov_b64_e32 v[6:7], 0
	v_mov_b64_e32 v[8:9], 0
	v_mov_b64_e32 v[10:11], 0
	v_mov_b64_e32 v[12:13], 0
	v_mov_b64_e32 v[14:15], 0
	v_mov_b64_e32 v[16:17], 0
	v_mov_b64_e32 v[18:19], 0
	v_mov_b64_e32 v[20:21], 0
	v_mov_b64_e32 v[22:23], 0
	v_mov_b64_e32 v[24:25], 0
	v_mov_b64_e32 v[26:27], 0
	v_mov_b64_e32 v[28:29], 0
	v_mov_b64_e32 v[30:31], 0
	v_mov_b64_e32 v[32:33], 0
	v_mov_b64_e32 v[34:35], 0
	v_mov_b64_e32 v[36:37], 0
	v_mov_b64_e32 v[38:39], 0
	v_mov_b64_e32 v[40:41], 0
	v_mov_b64_e32 v[42:43], 0
	v_mov_b64_e32 v[44:45], 0
	v_mov_b64_e32 v[46:47], 0
	v_mov_b64_e32 v[48:49], 0
	v_mov_b64_e32 v[50:51], 0
	v_mov_b64_e32 v[52:53], 0
	v_mov_b64_e32 v[54:55], 0
	v_mov_b64_e32 v[56:57], 0
	v_mov_b64_e32 v[58:59], 0
	v_mov_b64_e32 v[60:61], 0
	v_mov_b64_e32 v[62:63], 0
	v_mov_b64_e32 v[64:65], 0
	v_mov_b64_e32 v[66:67], 0
	v_mov_b64_e32 v[68:69], 0
	v_mov_b64_e32 v[70:71], 0
	v_mov_b64_e32 v[72:73], 0
	v_mov_b64_e32 v[74:75], 0
	v_mov_b64_e32 v[76:77], 0
	v_mov_b64_e32 v[78:79], 0
	v_mov_b64_e32 v[80:81], 0
	v_mov_b64_e32 v[82:83], 0
	v_mov_b64_e32 v[84:85], 0
	v_mov_b64_e32 v[86:87], 0
	v_mov_b64_e32 v[88:89], 0
	v_mov_b64_e32 v[90:91], 0
	v_mov_b64_e32 v[92:93], 0
	v_mov_b64_e32 v[94:95], 0
	v_mov_b64_e32 v[96:97], 0
	v_mov_b64_e32 v[98:99], 0
	v_mov_b64_e32 v[100:101], 0
	v_mov_b64_e32 v[102:103], 0
	v_mov_b64_e32 v[104:105], 0
	v_mov_b64_e32 v[106:107], 0
	v_mov_b64_e32 v[108:109], 0
	v_mov_b64_e32 v[110:111], 0
	v_mov_b64_e32 v[116:117], 0
	v_mov_b64_e32 v[118:119], 0
	v_mov_b64_e32 v[120:121], 0
	v_mov_b64_e32 v[122:123], 0
	v_mov_b64_e32 v[128:129], 0
	v_mov_b64_e32 v[130:131], 0
	v_mov_b64_e32 v[132:133], 0
	v_mov_b64_e32 v[134:135], 0
	s_addc_u32 s71, s71, 0
	s_mov_b32 s73, -2
	s_waitcnt lgkmcnt(0)

; template <class Epi, class Sched, bool ALIGN_EPI = false, bool SP2 = false>
; __device__ __forceinline__ void gemm_phase(PG8_LAS unsigned char* lds, const Gemm g, const Sched& S, const Epi& E) {
;     ...
;         const bool has_next = S.next(ui + 1, nxt);
;         const char* nA = has_next ? (const char*)g.A + (size_t)nxt.pm * tstepA : cA; const char* nB = has_next ? (const char*)g.Bt + (size_t)nxt.pn * tstepB : cB;
;     ...
; #pragma unroll
;         for (int a = 0; a < 2; ++a)
; #pragma unroll
;             for (int b = 0; b < 2; ++b)
; #pragma unroll
;                 for (int m = 0; m < 4; ++m)
; #pragma unroll
;                     for (int n = 0; n < 2; ++n) acc[a][b][m][n] = (f32x4){0.f, 0.f, 0.f, 0.f};
;         cur = nxt; cA = nA; cB = nB; ++ui;
.LBB0_314:
	s_ashr_i32 s63, s62, 31
	s_lshl_b64 s[8:9], s[62:63], 19
	s_add_u32 s68, s12, s8
	s_addc_u32 s69, s13, s9
	s_and_b64 s[8:9], s[2:3], exec
	s_cselect_b32 s7, s69, s5
	s_cselect_b32 s63, s68, s4
	s_ashr_i32 s61, s60, 31
	s_lshl_b64 s[8:9], s[60:61], 19
	s_add_u32 s70, s87, s8
	s_addc_u32 s71, s88, s9
	s_and_b64 s[8:9], s[2:3], exec
	s_cselect_b32 s61, s71, s75
	s_cselect_b32 s73, s70, s74
	s_add_u32 s4, s4, 0x10000
	s_addc_u32 s5, s5, 0
	s_add_u32 s74, s74, 0x10000
	v_mov_b64_e32 v[4:5], 0
	v_mov_b64_e32 v[6:7], 0
	v_mov_b64_e32 v[8:9], 0
	v_mov_b64_e32 v[10:11], 0
	v_mov_b64_e32 v[12:13], 0
	v_mov_b64_e32 v[14:15], 0
	v_mov_b64_e32 v[16:17], 0
	v_mov_b64_e32 v[18:19], 0
	v_mov_b64_e32 v[20:21], 0
	v_mov_b64_e32 v[22:23], 0
	v_mov_b64_e32 v[24:25], 0
	v_mov_b64_e32 v[26:27], 0
	v_mov_b64_e32 v[28:29], 0
	v_mov_b64_e32 v[30:31], 0
	v_mov_b64_e32 v[32:33], 0
	v_mov_b64_e32 v[34:35], 0
	v_mov_b64_e32 v[36:37], 0
	v_mov_b64_e32 v[38:39], 0
	v_mov_b64_e32 v[40:41], 0
	v_mov_b64_e32 v[42:43], 0
	v_mov_b64_e32 v[44:45], 0
	v_mov_b64_e32 v[46:47], 0
	v_mov_b64_e32 v[48:49], 0
	v_mov_b64_e32 v[50:51], 0
	v_mov_b64_e32 v[52:53], 0
	v_mov_b64_e32 v[54:55], 0
	v_mov_b64_e32 v[56:57], 0
	v_mov_b64_e32 v[58:59], 0
	v_mov_b64_e32 v[60:61], 0
	v_mov_b64_e32 v[62:63], 0
	v_mov_b64_e32 v[64:65], 0
	v_mov_b64_e32 v[66:67], 0
	v_mov_b64_e32 v[68:69], 0
	v_mov_b64_e32 v[70:71], 0
	v_mov_b64_e32 v[72:73], 0
	v_mov_b64_e32 v[74:75], 0
	v_mov_b64_e32 v[76:77], 0
	v_mov_b64_e32 v[78:79], 0
	v_mov_b64_e32 v[80:81], 0
	v_mov_b64_e32 v[82:83], 0
	v_mov_b64_e32 v[84:85], 0
	v_mov_b64_e32 v[86:87], 0
	v_mov_b64_e32 v[88:89], 0
	v_mov_b64_e32 v[90:91], 0
	v_mov_b64_e32 v[92:93], 0
	v_mov_b64_e32 v[94:95], 0
	v_mov_b64_e32 v[96:97], 0
	v_mov_b64_e32 v[98:99], 0
	v_mov_b64_e32 v[100:101], 0
	v_mov_b64_e32 v[102:103], 0
	v_mov_b64_e32 v[104:105], 0
	v_mov_b64_e32 v[106:107], 0
	v_mov_b64_e32 v[108:109], 0
	v_mov_b64_e32 v[110:111], 0
	v_mov_b64_e32 v[112:113], 0
	v_mov_b64_e32 v[114:115], 0
	v_mov_b64_e32 v[116:117], 0
	v_mov_b64_e32 v[118:119], 0
	v_mov_b64_e32 v[120:121], 0
	v_mov_b64_e32 v[122:123], 0
	v_mov_b64_e32 v[124:125], 0
	v_mov_b64_e32 v[126:127], 0
	v_mov_b64_e32 v[128:129], 0
	v_mov_b64_e32 v[130:131], 0
	s_addc_u32 s75, s75, 0
	s_mov_b32 s76, -2

; template <class Epi, class Sched, bool ALIGN_EPI = false, bool SP2 = false>
; __device__ __forceinline__ void gemm_phase(PG8_LAS unsigned char* lds, const Gemm g, const Sched& S, const Epi& E) {
;     ...
;         const bool has_next = S.next(ui + 1, nxt);
;         const char* nA = has_next ? (const char*)g.A + (size_t)nxt.pm * tstepA : cA; const char* nB = has_next ? (const char*)g.Bt + (size_t)nxt.pn * tstepB : cB;
;     ...
; #pragma unroll
;         for (int a = 0; a < 2; ++a)
; #pragma unroll
;             for (int b = 0; b < 2; ++b)
; #pragma unroll
;                 for (int m = 0; m < 4; ++m)
; #pragma unroll
;                     for (int n = 0; n < 2; ++n) acc[a][b][m][n] = (f32x4){0.f, 0.f, 0.f, 0.f};
;         cur = nxt; cA = nA; cB = nB; ++ui;
.LBB0_645:
	s_ashr_i32 s61, s60, 31
	s_lshl_b64 s[8:9], s[60:61], 19
	s_add_u32 s64, s85, s8
	s_addc_u32 s65, s86, s9
	s_and_b64 s[0:1], s[0:1], exec
	s_cselect_b32 s61, s65, s67
	s_cselect_b32 s90, s64, s66
	s_add_u32 s91, s66, 0x10000
	s_addc_u32 s92, s67, 0
	s_add_u32 s0, s68, 0xf0080
	v_mov_b64_e32 v[0:1], 0
	v_mov_b64_e32 v[2:3], 0
	v_mov_b64_e32 v[4:5], 0
	v_mov_b64_e32 v[6:7], 0
	v_mov_b64_e32 v[8:9], 0
	v_mov_b64_e32 v[10:11], 0
	v_mov_b64_e32 v[12:13], 0
	v_mov_b64_e32 v[14:15], 0
	v_mov_b64_e32 v[16:17], 0
	v_mov_b64_e32 v[18:19], 0
	v_mov_b64_e32 v[20:21], 0
	v_mov_b64_e32 v[22:23], 0
	v_mov_b64_e32 v[24:25], 0
	v_mov_b64_e32 v[26:27], 0
	v_mov_b64_e32 v[28:29], 0
	v_mov_b64_e32 v[30:31], 0
	v_mov_b64_e32 v[32:33], 0
	v_mov_b64_e32 v[34:35], 0
	v_mov_b64_e32 v[36:37], 0
	v_mov_b64_e32 v[38:39], 0
	v_mov_b64_e32 v[40:41], 0
	v_mov_b64_e32 v[42:43], 0
	v_mov_b64_e32 v[44:45], 0
	v_mov_b64_e32 v[46:47], 0
	v_mov_b64_e32 v[48:49], 0
	v_mov_b64_e32 v[50:51], 0
	v_mov_b64_e32 v[52:53], 0
	v_mov_b64_e32 v[54:55], 0
	v_mov_b64_e32 v[56:57], 0
	v_mov_b64_e32 v[58:59], 0
	v_mov_b64_e32 v[60:61], 0
	v_mov_b64_e32 v[62:63], 0
	v_mov_b64_e32 v[64:65], 0
	v_mov_b64_e32 v[66:67], 0
	v_mov_b64_e32 v[68:69], 0
	v_mov_b64_e32 v[70:71], 0
	v_mov_b64_e32 v[72:73], 0
	v_mov_b64_e32 v[74:75], 0
	v_mov_b64_e32 v[76:77], 0
	v_mov_b64_e32 v[78:79], 0
	v_mov_b64_e32 v[80:81], 0
	v_mov_b64_e32 v[82:83], 0
	v_mov_b64_e32 v[84:85], 0
	v_mov_b64_e32 v[86:87], 0
	v_mov_b64_e32 v[88:89], 0
	v_mov_b64_e32 v[90:91], 0
	v_mov_b64_e32 v[92:93], 0
	v_mov_b64_e32 v[94:95], 0
	v_mov_b64_e32 v[96:97], 0
	v_mov_b64_e32 v[98:99], 0
	v_mov_b64_e32 v[100:101], 0
	v_mov_b64_e32 v[102:103], 0
	v_mov_b64_e32 v[104:105], 0
	v_mov_b64_e32 v[106:107], 0
	v_mov_b64_e32 v[108:109], 0
	v_mov_b64_e32 v[110:111], 0
	v_mov_b64_e32 v[112:113], 0
	v_mov_b64_e32 v[114:115], 0
	v_mov_b64_e32 v[116:117], 0
	v_mov_b64_e32 v[118:119], 0
	v_mov_b64_e32 v[120:121], 0
	v_mov_b64_e32 v[122:123], 0
	v_mov_b64_e32 v[124:125], 0
	v_mov_b64_e32 v[126:127], 0
	s_addc_u32 s1, s69, 0
	s_mov_b32 s68, -2

; template <class Epi, class Sched, bool ALIGN_EPI = false, bool SP2 = false>
; __device__ __forceinline__ void gemm_phase(PG8_LAS unsigned char* lds, const Gemm g, const Sched& S, const Epi& E) {
;     ...
;         const bool has_next = S.next(ui + 1, nxt);
;         const char* nA = has_next ? (const char*)g.A + (size_t)nxt.pm * tstepA : cA; const char* nB = has_next ? (const char*)g.Bt + (size_t)nxt.pn * tstepB : cB;
;     ...
; #pragma unroll
;         for (int a = 0; a < 2; ++a)
; #pragma unroll
;             for (int b = 0; b < 2; ++b)
; #pragma unroll
;                 for (int m = 0; m < 4; ++m)
; #pragma unroll
;                     for (int n = 0; n < 2; ++n) acc[a][b][m][n] = (f32x4){0.f, 0.f, 0.f, 0.f};
;         cur = nxt; cA = nA; cB = nB; ++ui;
.LBB0_669:
	s_ashr_i32 s57, s56, 31
	s_lshl_b64 s[8:9], s[56:57], 18
	s_add_u32 s58, s30, s8
	s_addc_u32 s59, s31, s9
	s_and_b64 s[8:9], s[2:3], exec
	s_cselect_b32 s57, s59, s67
	s_cselect_b32 s68, s58, s66
	s_ashr_i32 s55, s54, 31
	s_lshl_b64 s[8:9], s[54:55], 18
	v_readlane_b32 s60, v246, 7
	v_readlane_b32 s61, v246, 8
	s_add_u32 s60, s60, s8
	s_addc_u32 s61, s61, s9
	s_and_b64 s[8:9], s[2:3], exec
	s_cselect_b32 s55, s61, s65
	s_cselect_b32 s69, s60, s64
	s_add_u32 s82, s64, 0x10000
	s_addc_u32 s85, s65, 0
	s_add_u32 s64, s66, 0x20080
	v_mov_b64_e32 v[0:1], 0
	v_mov_b64_e32 v[2:3], 0
	v_mov_b64_e32 v[4:5], 0
	v_mov_b64_e32 v[6:7], 0
	v_mov_b64_e32 v[8:9], 0
	v_mov_b64_e32 v[10:11], 0
	v_mov_b64_e32 v[12:13], 0
	v_mov_b64_e32 v[14:15], 0
	v_mov_b64_e32 v[16:17], 0
	v_mov_b64_e32 v[18:19], 0
	v_mov_b64_e32 v[20:21], 0
	v_mov_b64_e32 v[22:23], 0
	v_mov_b64_e32 v[24:25], 0
	v_mov_b64_e32 v[26:27], 0
	v_mov_b64_e32 v[28:29], 0
	v_mov_b64_e32 v[30:31], 0
	v_mov_b64_e32 v[32:33], 0
	v_mov_b64_e32 v[34:35], 0
	v_mov_b64_e32 v[36:37], 0
	v_mov_b64_e32 v[38:39], 0
	v_mov_b64_e32 v[40:41], 0
	v_mov_b64_e32 v[42:43], 0
	v_mov_b64_e32 v[44:45], 0
	v_mov_b64_e32 v[46:47], 0
	v_mov_b64_e32 v[48:49], 0
	v_mov_b64_e32 v[50:51], 0
	v_mov_b64_e32 v[52:53], 0
	v_mov_b64_e32 v[54:55], 0
	v_mov_b64_e32 v[56:57], 0
	v_mov_b64_e32 v[58:59], 0
	v_mov_b64_e32 v[60:61], 0
	v_mov_b64_e32 v[62:63], 0
	v_mov_b64_e32 v[64:65], 0
	v_mov_b64_e32 v[66:67], 0
	v_mov_b64_e32 v[68:69], 0
	v_mov_b64_e32 v[70:71], 0
	v_mov_b64_e32 v[72:73], 0
	v_mov_b64_e32 v[74:75], 0
	v_mov_b64_e32 v[76:77], 0
	v_mov_b64_e32 v[78:79], 0
	v_mov_b64_e32 v[80:81], 0
	v_mov_b64_e32 v[82:83], 0
	v_mov_b64_e32 v[84:85], 0
	v_mov_b64_e32 v[86:87], 0
	v_mov_b64_e32 v[88:89], 0
	v_mov_b64_e32 v[90:91], 0
	v_mov_b64_e32 v[92:93], 0
	v_mov_b64_e32 v[94:95], 0
	v_mov_b64_e32 v[96:97], 0
	v_mov_b64_e32 v[98:99], 0
	v_mov_b64_e32 v[100:101], 0
	v_mov_b64_e32 v[102:103], 0
	v_mov_b64_e32 v[104:105], 0
	v_mov_b64_e32 v[106:107], 0
	v_mov_b64_e32 v[112:113], 0
	v_mov_b64_e32 v[114:115], 0
	v_mov_b64_e32 v[116:117], 0
	v_mov_b64_e32 v[118:119], 0
	v_mov_b64_e32 v[120:121], 0
	v_mov_b64_e32 v[122:123], 0
	v_mov_b64_e32 v[124:125], 0
	v_mov_b64_e32 v[126:127], 0
	v_mov_b64_e32 v[128:129], 0
	v_mov_b64_e32 v[130:131], 0
	s_addc_u32 s65, s67, 0
	s_mov_b32 s86, -2

; template <class Epi, class Sched, bool ALIGN_EPI = false, bool SP2 = false>
; __device__ __forceinline__ void gemm_phase(PG8_LAS unsigned char* lds, const Gemm g, const Sched& S, const Epi& E) {
;     ...
;         const bool has_next = S.next(ui + 1, nxt);
;         const char* nA = has_next ? (const char*)g.A + (size_t)nxt.pm * tstepA : cA; const char* nB = has_next ? (const char*)g.Bt + (size_t)nxt.pn * tstepB : cB;
;     ...
; #pragma unroll
;         for (int a = 0; a < 2; ++a)
; #pragma unroll
;             for (int b = 0; b < 2; ++b)
; #pragma unroll
;                 for (int m = 0; m < 4; ++m)
; #pragma unroll
;                     for (int n = 0; n < 2; ++n) acc[a][b][m][n] = (f32x4){0.f, 0.f, 0.f, 0.f};
;         cur = nxt; cA = nA; cB = nB; ++ui;
.LBB0_750:
	s_ashr_i32 s59, s58, 31
	s_lshl_b64 s[60:61], s[58:59], 19
	s_add_u32 s60, s6, s60
	s_addc_u32 s61, s7, s61
	s_and_b64 s[62:63], s[4:5], exec
	s_cselect_b32 s59, s61, s69
	s_cselect_b32 s65, s60, s68
	s_ashr_i32 s57, s56, 31
	s_lshl_b64 s[62:63], s[56:57], 19
	s_add_u32 s62, s93, s62
	s_addc_u32 s63, s84, s63
	s_and_b64 s[72:73], s[4:5], exec
	s_cselect_b32 s57, s63, s71
	s_cselect_b32 s67, s62, s70
	s_add_u32 s68, s68, 0x10000
	s_addc_u32 s69, s69, 0
	s_add_u32 s70, s70, 0x10000
	v_mov_b64_e32 v[0:1], 0
	v_mov_b64_e32 v[2:3], 0
	v_mov_b64_e32 v[4:5], 0
	v_mov_b64_e32 v[6:7], 0
	v_mov_b64_e32 v[8:9], 0
	v_mov_b64_e32 v[10:11], 0
	v_mov_b64_e32 v[12:13], 0
	v_mov_b64_e32 v[14:15], 0
	v_mov_b64_e32 v[16:17], 0
	v_mov_b64_e32 v[18:19], 0
	v_mov_b64_e32 v[20:21], 0
	v_mov_b64_e32 v[22:23], 0
	v_mov_b64_e32 v[24:25], 0
	v_mov_b64_e32 v[26:27], 0
	v_mov_b64_e32 v[28:29], 0
	v_mov_b64_e32 v[30:31], 0
	v_mov_b64_e32 v[32:33], 0
	v_mov_b64_e32 v[34:35], 0
	v_mov_b64_e32 v[36:37], 0
	v_mov_b64_e32 v[38:39], 0
	v_mov_b64_e32 v[40:41], 0
	v_mov_b64_e32 v[42:43], 0
	v_mov_b64_e32 v[44:45], 0
	v_mov_b64_e32 v[46:47], 0
	v_mov_b64_e32 v[48:49], 0
	v_mov_b64_e32 v[50:51], 0
	v_mov_b64_e32 v[52:53], 0
	v_mov_b64_e32 v[54:55], 0
	v_mov_b64_e32 v[56:57], 0
	v_mov_b64_e32 v[58:59], 0
	v_mov_b64_e32 v[60:61], 0
	v_mov_b64_e32 v[62:63], 0
	v_mov_b64_e32 v[64:65], 0
	v_mov_b64_e32 v[66:67], 0
	v_mov_b64_e32 v[68:69], 0
	v_mov_b64_e32 v[70:71], 0
	v_mov_b64_e32 v[72:73], 0
	v_mov_b64_e32 v[74:75], 0
	v_mov_b64_e32 v[76:77], 0
	v_mov_b64_e32 v[78:79], 0
	v_mov_b64_e32 v[80:81], 0
	v_mov_b64_e32 v[82:83], 0
	v_mov_b64_e32 v[84:85], 0
	v_mov_b64_e32 v[86:87], 0
	v_mov_b64_e32 v[88:89], 0
	v_mov_b64_e32 v[90:91], 0
	v_mov_b64_e32 v[92:93], 0
	v_mov_b64_e32 v[94:95], 0
	v_mov_b64_e32 v[96:97], 0
	v_mov_b64_e32 v[98:99], 0
	v_mov_b64_e32 v[100:101], 0
	v_mov_b64_e32 v[102:103], 0
	v_mov_b64_e32 v[104:105], 0
	v_mov_b64_e32 v[106:107], 0
	v_mov_b64_e32 v[108:109], 0
	v_mov_b64_e32 v[110:111], 0
	v_mov_b64_e32 v[112:113], 0
	v_mov_b64_e32 v[114:115], 0
	v_mov_b64_e32 v[116:117], 0
	v_mov_b64_e32 v[118:119], 0
	v_mov_b64_e32 v[120:121], 0
	v_mov_b64_e32 v[122:123], 0
	v_mov_b64_e32 v[124:125], 0
	v_mov_b64_e32 v[126:127], 0
	s_addc_u32 s71, s71, 0
	s_mov_b32 s72, -2
	s_waitcnt lgkmcnt(0)

; template <class Epi, class Sched, bool ALIGN_EPI = false, bool SP2 = false>
; __device__ __forceinline__ void gemm_phase(PG8_LAS unsigned char* lds, const Gemm g, const Sched& S, const Epi& E) {
;     ...
;         const bool has_next = S.next(ui + 1, nxt);
;         const char* nA = has_next ? (const char*)g.A + (size_t)nxt.pm * tstepA : cA; const char* nB = has_next ? (const char*)g.Bt + (size_t)nxt.pn * tstepB : cB;
;     ...
; #pragma unroll
;         for (int a = 0; a < 2; ++a)
; #pragma unroll
;             for (int b = 0; b < 2; ++b)
; #pragma unroll
;                 for (int m = 0; m < 4; ++m)
; #pragma unroll
;                     for (int n = 0; n < 2; ++n) acc[a][b][m][n] = (f32x4){0.f, 0.f, 0.f, 0.f};
;         cur = nxt; cA = nA; cB = nB; ++ui;
.LBB0_837:
	s_ashr_i32 s55, s54, 31
	s_lshl_b64 s[56:57], s[54:55], 19
	s_add_u32 s56, s12, s56
	s_addc_u32 s57, s13, s57
	s_and_b64 s[58:59], s[2:3], exec
	s_cselect_b32 s55, s57, s63
	s_cselect_b32 s80, s56, s62
	s_ashr_i32 s53, s52, 31
	s_lshl_b64 s[58:59], s[52:53], 19
	s_add_u32 s58, s33, s58
	s_addc_u32 s59, s83, s59
	s_and_b64 s[78:79], s[2:3], exec
	s_cselect_b32 s53, s59, s65
	s_cselect_b32 s81, s58, s64
	s_add_u32 s62, s62, 0x10000
	s_addc_u32 s63, s63, 0
	s_add_u32 s64, s64, 0x10000
	v_mov_b64_e32 v[0:1], 0
	v_mov_b64_e32 v[2:3], 0
	v_mov_b64_e32 v[4:5], 0
	v_mov_b64_e32 v[6:7], 0
	v_mov_b64_e32 v[8:9], 0
	v_mov_b64_e32 v[10:11], 0
	v_mov_b64_e32 v[12:13], 0
	v_mov_b64_e32 v[14:15], 0
	v_mov_b64_e32 v[16:17], 0
	v_mov_b64_e32 v[18:19], 0
	v_mov_b64_e32 v[20:21], 0
	v_mov_b64_e32 v[22:23], 0
	v_mov_b64_e32 v[24:25], 0
	v_mov_b64_e32 v[26:27], 0
	v_mov_b64_e32 v[28:29], 0
	v_mov_b64_e32 v[30:31], 0
	v_mov_b64_e32 v[32:33], 0
	v_mov_b64_e32 v[34:35], 0
	v_mov_b64_e32 v[36:37], 0
	v_mov_b64_e32 v[38:39], 0
	v_mov_b64_e32 v[40:41], 0
	v_mov_b64_e32 v[42:43], 0
	v_mov_b64_e32 v[44:45], 0
	v_mov_b64_e32 v[46:47], 0
	v_mov_b64_e32 v[48:49], 0
	v_mov_b64_e32 v[50:51], 0
	v_mov_b64_e32 v[52:53], 0
	v_mov_b64_e32 v[54:55], 0
	v_mov_b64_e32 v[56:57], 0
	v_mov_b64_e32 v[58:59], 0
	v_mov_b64_e32 v[60:61], 0
	v_mov_b64_e32 v[62:63], 0
	v_mov_b64_e32 v[64:65], 0
	v_mov_b64_e32 v[66:67], 0
	v_mov_b64_e32 v[68:69], 0
	v_mov_b64_e32 v[70:71], 0
	v_mov_b64_e32 v[72:73], 0
	v_mov_b64_e32 v[74:75], 0
	v_mov_b64_e32 v[76:77], 0
	v_mov_b64_e32 v[78:79], 0
	v_mov_b64_e32 v[80:81], 0
	v_mov_b64_e32 v[82:83], 0
	v_mov_b64_e32 v[84:85], 0
	v_mov_b64_e32 v[86:87], 0
	v_mov_b64_e32 v[88:89], 0
	v_mov_b64_e32 v[90:91], 0
	v_mov_b64_e32 v[92:93], 0
	v_mov_b64_e32 v[94:95], 0
	v_mov_b64_e32 v[96:97], 0
	v_mov_b64_e32 v[98:99], 0
	v_mov_b64_e32 v[100:101], 0
	v_mov_b64_e32 v[102:103], 0
	v_mov_b64_e32 v[104:105], 0
	v_mov_b64_e32 v[106:107], 0
	v_mov_b64_e32 v[108:109], 0
	v_mov_b64_e32 v[110:111], 0
	v_mov_b64_e32 v[112:113], 0
	v_mov_b64_e32 v[114:115], 0
	v_mov_b64_e32 v[116:117], 0
	v_mov_b64_e32 v[118:119], 0
	v_mov_b64_e32 v[120:121], 0
	v_mov_b64_e32 v[122:123], 0
	v_mov_b64_e32 v[124:125], 0
	v_mov_b64_e32 v[126:127], 0
	s_addc_u32 s65, s65, 0
	s_mov_b32 s82, -2

; template <class Epi, class Sched, bool ALIGN_EPI = false, bool SP2 = false>
; __device__ __forceinline__ void gemm_phase(PG8_LAS unsigned char* lds, const Gemm g, const Sched& S, const Epi& E) {
;     ...
; #pragma unroll
;         for (int a = 0; a < 2; ++a)
; #pragma unroll
;             for (int b = 0; b < 2; ++b)
; #pragma unroll
;                 for (int m = 0; m < 4; ++m)
; #pragma unroll
;                     for (int n = 0; n < 2; ++n) acc[a][b][m][n] = (f32x4){0.f, 0.f, 0.f, 0.f};
;         cur = nxt; cA = nA; cB = nB; ++ui;
.LBB0_923:
	s_add_u32 s6, s6, 0x10000
	s_addc_u32 s7, s7, 0
	s_add_u32 s64, s64, 0x10000
	v_mov_b64_e32 v[0:1], 0
	v_mov_b64_e32 v[2:3], 0
	v_mov_b64_e32 v[4:5], 0
	v_mov_b64_e32 v[6:7], 0
	v_mov_b64_e32 v[8:9], 0
	v_mov_b64_e32 v[10:11], 0
	v_mov_b64_e32 v[12:13], 0
	v_mov_b64_e32 v[14:15], 0
	v_mov_b64_e32 v[16:17], 0
	v_mov_b64_e32 v[18:19], 0
	v_mov_b64_e32 v[20:21], 0
	v_mov_b64_e32 v[22:23], 0
	v_mov_b64_e32 v[24:25], 0
	v_mov_b64_e32 v[26:27], 0
	v_mov_b64_e32 v[28:29], 0
	v_mov_b64_e32 v[30:31], 0
	v_mov_b64_e32 v[32:33], 0
	v_mov_b64_e32 v[34:35], 0
	v_mov_b64_e32 v[36:37], 0
	v_mov_b64_e32 v[38:39], 0
	v_mov_b64_e32 v[40:41], 0
	v_mov_b64_e32 v[42:43], 0
	v_mov_b64_e32 v[44:45], 0
	v_mov_b64_e32 v[46:47], 0
	v_mov_b64_e32 v[48:49], 0
	v_mov_b64_e32 v[50:51], 0
	v_mov_b64_e32 v[52:53], 0
	v_mov_b64_e32 v[54:55], 0
	v_mov_b64_e32 v[56:57], 0
	v_mov_b64_e32 v[58:59], 0
	v_mov_b64_e32 v[60:61], 0
	v_mov_b64_e32 v[62:63], 0
	v_mov_b64_e32 v[64:65], 0
	v_mov_b64_e32 v[66:67], 0
	v_mov_b64_e32 v[68:69], 0
	v_mov_b64_e32 v[70:71], 0
	v_mov_b64_e32 v[72:73], 0
	v_mov_b64_e32 v[74:75], 0
	v_mov_b64_e32 v[76:77], 0
	v_mov_b64_e32 v[78:79], 0
	v_mov_b64_e32 v[80:81], 0
	v_mov_b64_e32 v[82:83], 0
	v_mov_b64_e32 v[88:89], 0
	v_mov_b64_e32 v[90:91], 0
	v_mov_b64_e32 v[96:97], 0
	v_mov_b64_e32 v[98:99], 0
	v_mov_b64_e32 v[100:101], 0
	v_mov_b64_e32 v[102:103], 0
	v_mov_b64_e32 v[108:109], 0
	v_mov_b64_e32 v[110:111], 0
	v_mov_b64_e32 v[112:113], 0
	v_mov_b64_e32 v[114:115], 0
	v_mov_b64_e32 v[120:121], 0
	v_mov_b64_e32 v[122:123], 0
	v_mov_b64_e32 v[124:125], 0
	v_mov_b64_e32 v[126:127], 0
	v_mov_b64_e32 v[132:133], 0
	v_mov_b64_e32 v[134:135], 0
	v_mov_b64_e32 v[136:137], 0
	v_mov_b64_e32 v[138:139], 0
	v_mov_b64_e32 v[144:145], 0
	v_mov_b64_e32 v[146:147], 0
	v_mov_b64_e32 v[148:149], 0
	v_mov_b64_e32 v[150:151], 0
	s_addc_u32 s65, s65, 0
	s_mov_b32 s66, -2
	s_waitcnt lgkmcnt(0)

; template <class Epi, class Sched, bool ALIGN_EPI = false, bool SP2 = false>
; __device__ __forceinline__ void gemm_phase(PG8_LAS unsigned char* lds, const Gemm g, const Sched& S, const Epi& E) {
;     ...
; #pragma unroll
;         for (int a = 0; a < 2; ++a)
; #pragma unroll
;             for (int b = 0; b < 2; ++b)
; #pragma unroll
;                 for (int m = 0; m < 4; ++m)
; #pragma unroll
;                     for (int n = 0; n < 2; ++n) acc[a][b][m][n] = (f32x4){0.f, 0.f, 0.f, 0.f};
;         cur = nxt; cA = nA; cB = nB; ++ui;
.LBB0_1003:
	s_add_u32 s70, s70, 0x10000
	s_addc_u32 s71, s71, 0
	s_add_u32 s69, s72, 0x10000
	v_mov_b64_e32 v[0:1], 0
	v_mov_b64_e32 v[2:3], 0
	v_mov_b64_e32 v[4:5], 0
	v_mov_b64_e32 v[6:7], 0
	v_mov_b64_e32 v[8:9], 0
	v_mov_b64_e32 v[10:11], 0
	v_mov_b64_e32 v[12:13], 0
	v_mov_b64_e32 v[14:15], 0
	v_mov_b64_e32 v[16:17], 0
	v_mov_b64_e32 v[18:19], 0
	v_mov_b64_e32 v[20:21], 0
	v_mov_b64_e32 v[22:23], 0
	v_mov_b64_e32 v[24:25], 0
	v_mov_b64_e32 v[26:27], 0
	v_mov_b64_e32 v[28:29], 0
	v_mov_b64_e32 v[30:31], 0
	v_mov_b64_e32 v[32:33], 0
	v_mov_b64_e32 v[34:35], 0
	v_mov_b64_e32 v[36:37], 0
	v_mov_b64_e32 v[38:39], 0
	v_mov_b64_e32 v[40:41], 0
	v_mov_b64_e32 v[42:43], 0
	v_mov_b64_e32 v[44:45], 0
	v_mov_b64_e32 v[46:47], 0
	v_mov_b64_e32 v[48:49], 0
	v_mov_b64_e32 v[50:51], 0
	v_mov_b64_e32 v[52:53], 0
	v_mov_b64_e32 v[54:55], 0
	v_mov_b64_e32 v[56:57], 0
	v_mov_b64_e32 v[58:59], 0
	v_mov_b64_e32 v[60:61], 0
	v_mov_b64_e32 v[62:63], 0
	v_mov_b64_e32 v[64:65], 0
	v_mov_b64_e32 v[66:67], 0
	v_mov_b64_e32 v[68:69], 0
	v_mov_b64_e32 v[70:71], 0
	v_mov_b64_e32 v[72:73], 0
	v_mov_b64_e32 v[74:75], 0
	v_mov_b64_e32 v[76:77], 0
	v_mov_b64_e32 v[78:79], 0
	v_mov_b64_e32 v[80:81], 0
	v_mov_b64_e32 v[82:83], 0
	v_mov_b64_e32 v[84:85], 0
	v_mov_b64_e32 v[86:87], 0
	v_mov_b64_e32 v[88:89], 0
	v_mov_b64_e32 v[90:91], 0
	v_mov_b64_e32 v[92:93], 0
	v_mov_b64_e32 v[94:95], 0
	v_mov_b64_e32 v[96:97], 0
	v_mov_b64_e32 v[98:99], 0
	v_mov_b64_e32 v[100:101], 0
	v_mov_b64_e32 v[102:103], 0
	v_mov_b64_e32 v[104:105], 0
	v_mov_b64_e32 v[106:107], 0
	v_mov_b64_e32 v[108:109], 0
	v_mov_b64_e32 v[110:111], 0
	v_mov_b64_e32 v[112:113], 0
	v_mov_b64_e32 v[114:115], 0
	v_mov_b64_e32 v[116:117], 0
	v_mov_b64_e32 v[118:119], 0
	v_mov_b64_e32 v[120:121], 0
	v_mov_b64_e32 v[122:123], 0
	v_mov_b64_e32 v[124:125], 0
	v_mov_b64_e32 v[126:127], 0
	s_addc_u32 s72, s73, 0
	s_mov_b32 s73, -2
